# split-unit fixup pass unrolled (six loads in flight) on top of LRU bias fold + y_b cvt_pk
# speedup vs baseline: 1.0057x; 1.0057x over previous
; __device__ __forceinline__ unsigned pk2(float lo, float hi) { return f2bf(lo) | (f2bf(hi) << 16); }
; __device__ __forceinline__ float bflo(unsigned w) { return __uint_as_float(w << 16); }
; __device__ __forceinline__ float bfhi(unsigned w) { return __uint_as_float(w & 0xffff0000u); }
; __global__ void __launch_bounds__(NTHR, 2) hybrid_fwd(Params p) {
;     ...
;                 if (split && step == 1) {
;                     const bf16* P0 = (const bf16*)(ws + WS_HL); const bf16* P1 = P0 + (size_t)MT * DM; bf16* MG = (bf16*)(ws + WS_PP);
;                     for (int it = c * NTHR + (int)threadIdx.x; it < 1024 * 256; it += G * NTHR) { const size_t r = (size_t)(NP + (it >> 8)); const int c8 = (it & 255) * 8;
;                         const v4u a = *(const v4u*)(P0 + r * DM + c8), b = *(const v4u*)(P1 + r * DM + c8), gq = *(const v4u*)(PROJ + r * NC + C_MB + c8);
;                         v4u o;
;                         o.x = pk2(fmaxf(bflo(gq.x), 1e-30f) * (bflo(a.x) + bflo(b.x)), fmaxf(bfhi(gq.x), 1e-30f) * (bfhi(a.x) + bfhi(b.x)));
;                         o.y = pk2(fmaxf(bflo(gq.y), 1e-30f) * (bflo(a.y) + bflo(b.y)), fmaxf(bfhi(gq.y), 1e-30f) * (bfhi(a.y) + bfhi(b.y)));
;                         o.z = pk2(fmaxf(bflo(gq.z), 1e-30f) * (bflo(a.z) + bflo(b.z)), fmaxf(bfhi(gq.z), 1e-30f) * (bfhi(a.z) + bfhi(b.z)));
;                         o.w = pk2(fmaxf(bflo(gq.w), 1e-30f) * (bflo(a.w) + bflo(b.w)), fmaxf(bfhi(gq.w), 1e-30f) * (bfhi(a.w) + bfhi(b.w)));
;                         *(v4u*)(MG + r * DM + c8) = o; }
.LBB0_918:
	v_add_u32_e32 v26, 0x100000, v2
	v_add_u32_e32 v27, 0x20000, v3
	v_mov_b32_e32 v25, 0
	v_ashrrev_i32_e32 v0, 8, v3
	v_add_u32_e32 v12, 0x2000, v0
	v_ashrrev_i32_e32 v13, 31, v12
	v_and_b32_e32 v0, 0x7f8, v2
	v_mov_b64_e32 v[14:15], s[8:9]
	v_lshlrev_b64 v[16:17], 12, v[12:13]
	v_lshlrev_b32_e32 v0, 1, v0
	v_mad_i64_i32 v[12:13], s[2:3], v12, s25, v[14:15]
	v_lshl_add_u64 v[12:13], v[12:13], 0, v[0:1]
	v_lshl_add_u64 v[4:5], s[46:47], 0, v[16:17]
	v_lshl_add_u64 v[8:9], s[56:57], 0, v[16:17]
	v_add_co_u32_e32 v12, vcc, s22, v12
	v_lshl_add_u64 v[4:5], v[4:5], 0, v[0:1]
	v_lshl_add_u64 v[8:9], v[8:9], 0, v[0:1]
	v_addc_co_u32_e32 v13, vcc, 0, v13, vcc
	global_load_dwordx4 v[4:7], v[4:5], off
	global_load_dwordx4 v[8:11], v[8:9], off
	global_load_dwordx4 v[12:15], v[12:13], off
	v_ashrrev_i32_e32 v24, 8, v27
	v_add_u32_e32 v36, 0x2000, v24
	v_ashrrev_i32_e32 v37, 31, v36
	v_and_b32_e32 v24, 0x7f8, v26
	v_mov_b64_e32 v[38:39], s[8:9]
	v_lshlrev_b64 v[40:41], 12, v[36:37]
	v_lshlrev_b32_e32 v24, 1, v24
	v_mad_i64_i32 v[36:37], s[2:3], v36, s25, v[38:39]
	v_lshl_add_u64 v[36:37], v[36:37], 0, v[24:25]
	v_lshl_add_u64 v[28:29], s[46:47], 0, v[40:41]
	v_lshl_add_u64 v[32:33], s[56:57], 0, v[40:41]
	v_add_co_u32_e32 v36, vcc, s22, v36
	v_lshl_add_u64 v[28:29], v[28:29], 0, v[24:25]
	v_lshl_add_u64 v[32:33], v[32:33], 0, v[24:25]
	v_addc_co_u32_e32 v37, vcc, 0, v37, vcc
	global_load_dwordx4 v[28:31], v[28:29], off
	global_load_dwordx4 v[32:35], v[32:33], off
	global_load_dwordx4 v[36:39], v[36:37], off
	s_waitcnt lgkmcnt(0)
	s_waitcnt vmcnt(5)
	v_lshlrev_b32_e32 v21, 16, v5
	v_lshlrev_b32_e32 v20, 16, v4
	s_waitcnt vmcnt(4)
	v_lshlrev_b32_e32 v23, 16, v9
	v_lshlrev_b32_e32 v22, 16, v8
	s_waitcnt vmcnt(3)
	v_lshlrev_b32_e32 v18, 16, v12
	v_and_b32_e32 v12, 0xffff0000, v12
	v_lshlrev_b32_e32 v19, 16, v13
	v_and_b32_e32 v13, 0xffff0000, v13
	v_and_b32_e32 v5, 0xffff0000, v5
	v_and_b32_e32 v4, 0xffff0000, v4
	v_and_b32_e32 v9, 0xffff0000, v9
	v_and_b32_e32 v8, 0xffff0000, v8
	v_max_f32_e32 v12, v12, v12
	v_max_f32_e32 v13, v13, v13
	v_pk_add_f32 v[4:5], v[4:5], v[8:9]
	v_and_b32_e32 v9, 0xffff0000, v14
	v_max_f32_e32 v18, v18, v18
	v_max_f32_e32 v12, 0xda24260, v12
	v_max_f32_e32 v19, v19, v19
	v_max_f32_e32 v13, 0xda24260, v13
	v_max_f32_e32 v9, v9, v9
	v_max_f32_e32 v18, 0xda24260, v18
	v_max_f32_e32 v19, 0xda24260, v19
	v_pk_add_f32 v[20:21], v[20:21], v[22:23]
	v_pk_mul_f32 v[4:5], v[4:5], v[12:13]
	v_lshlrev_b32_e32 v8, 16, v14
	v_max_f32_e32 v12, 0xda24260, v9
	v_lshlrev_b32_e32 v9, 16, v15
	v_and_b32_e32 v13, 0xffff0000, v15
	v_pk_mul_f32 v[18:19], v[20:21], v[18:19]
	v_max_f32_e32 v8, v8, v8
	v_max_f32_e32 v9, v9, v9
	v_max_f32_e32 v13, v13, v13
	v_lshlrev_b32_e32 v15, 16, v7
	v_lshlrev_b32_e32 v14, 16, v6
	v_lshlrev_b32_e32 v21, 16, v11
	v_lshlrev_b32_e32 v20, 16, v10
	v_and_b32_e32 v7, 0xffff0000, v7
	v_and_b32_e32 v6, 0xffff0000, v6
	v_and_b32_e32 v11, 0xffff0000, v11
	v_and_b32_e32 v10, 0xffff0000, v10
	v_max_f32_e32 v8, 0xda24260, v8
	v_max_f32_e32 v9, 0xda24260, v9
	v_max_f32_e32 v13, 0xda24260, v13
	v_pk_add_f32 v[14:15], v[14:15], v[20:21]
	v_pk_add_f32 v[6:7], v[6:7], v[10:11]
	v_pk_mul_f32 v[8:9], v[14:15], v[8:9]
	v_pk_mul_f32 v[6:7], v[6:7], v[12:13]
	v_bfe_u32 v12, v5, 16, 1
	v_bfe_u32 v13, v4, 16, 1
	v_add3_u32 v4, v4, v13, s26
	v_add3_u32 v5, v5, v12, s26
	v_bfe_u32 v12, v8, 16, 1
	v_bfe_u32 v13, v9, 16, 1
	v_bfe_u32 v10, v7, 16, 1
	v_bfe_u32 v11, v6, 16, 1
	v_add3_u32 v9, v9, v13, s26
	v_add3_u32 v8, v8, v12, s26
	v_add3_u32 v6, v6, v11, s26
	v_add3_u32 v7, v7, v10, s26
	v_bfe_u32 v10, v18, 16, 1
	v_bfe_u32 v11, v19, 16, 1
	v_lshrrev_b32_e32 v8, 16, v8
	v_lshrrev_b32_e32 v9, 16, v9
	v_add3_u32 v11, v19, v11, s26
	v_add3_u32 v10, v18, v10, s26
	v_and_or_b32 v7, v7, s24, v9
	v_and_or_b32 v6, v6, s24, v8
	v_lshl_add_u64 v[8:9], s[58:59], 0, v[16:17]
	v_lshrrev_b32_e32 v10, 16, v10
	v_lshrrev_b32_e32 v11, 16, v11
	v_lshl_add_u64 v[8:9], v[8:9], 0, v[0:1]
	v_and_or_b32 v5, v5, s24, v11
	v_and_or_b32 v4, v4, s24, v10
	global_store_dwordx4 v[8:9], v[4:7], off
	s_waitcnt lgkmcnt(0)
	s_waitcnt vmcnt(3)
	v_lshlrev_b32_e32 v45, 16, v29
	v_lshlrev_b32_e32 v44, 16, v28
	s_waitcnt vmcnt(2)
	v_lshlrev_b32_e32 v47, 16, v33
	v_lshlrev_b32_e32 v46, 16, v32
	s_waitcnt vmcnt(1)
	v_lshlrev_b32_e32 v42, 16, v36
	v_and_b32_e32 v36, 0xffff0000, v36
	v_lshlrev_b32_e32 v43, 16, v37
	v_and_b32_e32 v37, 0xffff0000, v37
	v_and_b32_e32 v29, 0xffff0000, v29
	v_and_b32_e32 v28, 0xffff0000, v28
	v_and_b32_e32 v33, 0xffff0000, v33
	v_and_b32_e32 v32, 0xffff0000, v32
	v_max_f32_e32 v36, v36, v36
	v_max_f32_e32 v37, v37, v37
	v_pk_add_f32 v[28:29], v[28:29], v[32:33]
	v_and_b32_e32 v33, 0xffff0000, v38
	v_max_f32_e32 v42, v42, v42
	v_max_f32_e32 v36, 0xda24260, v36
	v_max_f32_e32 v43, v43, v43
	v_max_f32_e32 v37, 0xda24260, v37
	v_max_f32_e32 v33, v33, v33
	v_max_f32_e32 v42, 0xda24260, v42
	v_max_f32_e32 v43, 0xda24260, v43
	v_pk_add_f32 v[44:45], v[44:45], v[46:47]
	v_pk_mul_f32 v[28:29], v[28:29], v[36:37]
	v_lshlrev_b32_e32 v32, 16, v38
	v_max_f32_e32 v36, 0xda24260, v33
	v_lshlrev_b32_e32 v33, 16, v39
	v_and_b32_e32 v37, 0xffff0000, v39
	v_pk_mul_f32 v[42:43], v[44:45], v[42:43]
	v_max_f32_e32 v32, v32, v32
	v_max_f32_e32 v33, v33, v33
	v_max_f32_e32 v37, v37, v37
	v_lshlrev_b32_e32 v39, 16, v31
	v_lshlrev_b32_e32 v38, 16, v30
	v_lshlrev_b32_e32 v45, 16, v35
	v_lshlrev_b32_e32 v44, 16, v34
	v_and_b32_e32 v31, 0xffff0000, v31
	v_and_b32_e32 v30, 0xffff0000, v30
	v_and_b32_e32 v35, 0xffff0000, v35
	v_and_b32_e32 v34, 0xffff0000, v34
	v_max_f32_e32 v32, 0xda24260, v32
	v_max_f32_e32 v33, 0xda24260, v33
	v_max_f32_e32 v37, 0xda24260, v37
	v_pk_add_f32 v[38:39], v[38:39], v[44:45]
	v_pk_add_f32 v[30:31], v[30:31], v[34:35]
	v_pk_mul_f32 v[32:33], v[38:39], v[32:33]
	v_pk_mul_f32 v[30:31], v[30:31], v[36:37]
	v_bfe_u32 v36, v29, 16, 1
	v_bfe_u32 v37, v28, 16, 1
	v_add3_u32 v28, v28, v37, s26
	v_add3_u32 v29, v29, v36, s26
	v_bfe_u32 v36, v32, 16, 1
	v_bfe_u32 v37, v33, 16, 1
	v_bfe_u32 v34, v31, 16, 1
	v_bfe_u32 v35, v30, 16, 1
	v_add3_u32 v33, v33, v37, s26
	v_add3_u32 v32, v32, v36, s26
	v_add3_u32 v30, v30, v35, s26
	v_add3_u32 v31, v31, v34, s26
	v_bfe_u32 v34, v42, 16, 1
	v_bfe_u32 v35, v43, 16, 1
	v_lshrrev_b32_e32 v32, 16, v32
	v_lshrrev_b32_e32 v33, 16, v33
	v_add3_u32 v35, v43, v35, s26
	v_add3_u32 v34, v42, v34, s26
	v_and_or_b32 v31, v31, s24, v33
	v_and_or_b32 v30, v30, s24, v32
	v_lshl_add_u64 v[32:33], s[58:59], 0, v[40:41]
	v_lshrrev_b32_e32 v34, 16, v34
	v_lshrrev_b32_e32 v35, 16, v35
	v_lshl_add_u64 v[32:33], v[32:33], 0, v[24:25]
	v_and_or_b32 v29, v29, s24, v35
	v_and_or_b32 v28, v28, s24, v34
	global_store_dwordx4 v[32:33], v[28:31], off
